# grid barrier seams 2-9: thread-0 path made straight-line (first-use discovery block dropped where the XCD counts are already known; single LDS read, no divisions)
# baseline (speedup 1.0000x reference)
; __device__ __forceinline__ unsigned xb_ld(unsigned* p)              { return __hip_atomic_load(p, __ATOMIC_RELAXED, __HIP_MEMORY_SCOPE_AGENT); }
; __device__ __forceinline__ unsigned xb_add(unsigned* p, unsigned v) { return __hip_atomic_fetch_add(p, v, __ATOMIC_RELAXED, __HIP_MEMORY_SCOPE_AGENT); }
; #define XB_SPIN(cond, bar) do { unsigned _sp = 0; while (cond) { __builtin_amdgcn_s_sleep(1); \
;     if ((++_sp & 255u) == 0u) { if (xb_ld(&(bar)[XB_TMO])) break; if (_sp > XB_SPIN_CAP) { atomicAdd(&(bar)[XB_TMO], 1u); break; } } } } while (0)
; __device__ __forceinline__ void xcd_barrier(const XcdBarrier& b) {
;     ...
;     if (threadIdx.x == 0) {
;         unsigned* bar = b.bar;
;         __builtin_amdgcn_s_waitcnt(0);
;         unsigned nloc = b.st[0], nx = b.st[1];
;         if (nloc == 0u) { xcd_barrier_complete(bar, b.x, nloc, nx); b.st[0] = nloc; b.st[1] = nx; }
;         const unsigned old = xb_add(&bar[XB_XSUB(b.x)], 1u);
;         const unsigned gen = old / nloc;
;         if (old + 1u == (gen + 1u) * nloc) {
;             __builtin_amdgcn_fence(__ATOMIC_RELEASE, "agent");
;             asm volatile("s_waitcnt vmcnt(0)" ::: "memory");
;             const unsigned og = xb_add(&bar[XB_TOP], 1u);
;             const unsigned tg = og / nx;
;             if (og + 1u == (tg + 1u) * nx) xb_add(&bar[XB_TOPGEN], 1u);
;             else XB_SPIN(xb_ld(&bar[XB_TOPGEN]) == tg, bar);
.Leinv_skip_1:
	s_mov_b64 s[0:1], exec
	v_readlane_b32 s2, v255, 2
	v_readlane_b32 s3, v255, 3
	s_and_b64 s[2:3], s[0:1], s[2:3]
	s_mov_b64 exec, s[2:3]
	s_cbranch_execz .LBB0_349
	v_mov_b32_e32 v0, 0x20000
	ds_read_b64 v[4:5], v0
	v_readlane_b32 s2, v255, 1
	s_lshl_b32 s2, s2, 8
	s_add_u32 s4, s96, s2
	s_addc_u32 s5, s97, 0
	v_mov_b32_e32 v3, 0x1000
	v_mov_b32_e32 v1, 1
	global_atomic_add v3, v3, v1, s[4:5] offset:1024 sc0
	v_mov_b32_e32 v2, 0x583000
	s_waitcnt lgkmcnt(0)
	v_mul_u32_u24_e32 v4, 2, v4
	v_mul_u32_u24_e32 v5, 2, v5
	s_nop 0
	v_readfirstlane_b32 s8, v5
	s_waitcnt vmcnt(0)
	v_readfirstlane_b32 s2, v3
	s_add_u32 s2, s2, 1
	v_cmp_ne_u32_e32 vcc, s2, v4
	s_cbranch_vccnz .Lgb_poll_1
	buffer_wbl2 sc1
	v_mov_b32_e32 v3, 1
	s_waitcnt vmcnt(0)
	global_atomic_add v2, v3, s[72:73] offset:1024

; __device__ __forceinline__ unsigned xb_ld(unsigned* p)              { return __hip_atomic_load(p, __ATOMIC_RELAXED, __HIP_MEMORY_SCOPE_AGENT); }
; __device__ __forceinline__ unsigned xb_add(unsigned* p, unsigned v) { return __hip_atomic_fetch_add(p, v, __ATOMIC_RELAXED, __HIP_MEMORY_SCOPE_AGENT); }
; #define XB_SPIN(cond, bar) do { unsigned _sp = 0; while (cond) { __builtin_amdgcn_s_sleep(1); \
;     if ((++_sp & 255u) == 0u) { if (xb_ld(&(bar)[XB_TMO])) break; if (_sp > XB_SPIN_CAP) { atomicAdd(&(bar)[XB_TMO], 1u); break; } } } } while (0)
; __device__ __forceinline__ void xcd_barrier(const XcdBarrier& b) {
;     ...
;     if (threadIdx.x == 0) {
;         unsigned* bar = b.bar;
;         __builtin_amdgcn_s_waitcnt(0);
;         unsigned nloc = b.st[0], nx = b.st[1];
;         if (nloc == 0u) { xcd_barrier_complete(bar, b.x, nloc, nx); b.st[0] = nloc; b.st[1] = nx; }
;         const unsigned old = xb_add(&bar[XB_XSUB(b.x)], 1u);
;         const unsigned gen = old / nloc;
;         if (old + 1u == (gen + 1u) * nloc) {
;             __builtin_amdgcn_fence(__ATOMIC_RELEASE, "agent");
;             asm volatile("s_waitcnt vmcnt(0)" ::: "memory");
;             const unsigned og = xb_add(&bar[XB_TOP], 1u);
;             const unsigned tg = og / nx;
;             if (og + 1u == (tg + 1u) * nx) xb_add(&bar[XB_TOPGEN], 1u);
;             else XB_SPIN(xb_ld(&bar[XB_TOPGEN]) == tg, bar);
.Leinv_skip_2:
	s_mov_b64 s[0:1], exec
	v_readlane_b32 s2, v255, 2
	v_readlane_b32 s3, v255, 3
	s_and_b64 s[2:3], s[0:1], s[2:3]
	s_mov_b64 exec, s[2:3]
	s_cbranch_execz .LBB0_447
	v_mov_b32_e32 v0, 0x20000
	ds_read_b64 v[4:5], v0
	v_readlane_b32 s2, v255, 1
	s_lshl_b32 s2, s2, 8
	s_add_u32 s4, s96, s2
	s_addc_u32 s5, s97, 0
	v_mov_b32_e32 v3, 0x1000
	v_mov_b32_e32 v1, 1
	global_atomic_add v3, v3, v1, s[4:5] offset:1024 sc0
	v_mov_b32_e32 v2, 0x583000
	s_waitcnt lgkmcnt(0)
	v_mul_u32_u24_e32 v4, 3, v4
	v_mul_u32_u24_e32 v5, 3, v5
	s_nop 0
	v_readfirstlane_b32 s8, v5
	s_waitcnt vmcnt(0)
	v_readfirstlane_b32 s2, v3
	s_add_u32 s2, s2, 1
	v_cmp_ne_u32_e32 vcc, s2, v4
	s_cbranch_vccnz .Lgb_poll_2
	buffer_wbl2 sc1
	v_mov_b32_e32 v3, 1
	s_waitcnt vmcnt(0)
	global_atomic_add v2, v3, s[72:73] offset:1024

; __device__ __forceinline__ unsigned xb_ld(unsigned* p)              { return __hip_atomic_load(p, __ATOMIC_RELAXED, __HIP_MEMORY_SCOPE_AGENT); }
; __device__ __forceinline__ unsigned xb_add(unsigned* p, unsigned v) { return __hip_atomic_fetch_add(p, v, __ATOMIC_RELAXED, __HIP_MEMORY_SCOPE_AGENT); }
; #define XB_SPIN(cond, bar) do { unsigned _sp = 0; while (cond) { __builtin_amdgcn_s_sleep(1); \
;     if ((++_sp & 255u) == 0u) { if (xb_ld(&(bar)[XB_TMO])) break; if (_sp > XB_SPIN_CAP) { atomicAdd(&(bar)[XB_TMO], 1u); break; } } } } while (0)
; __device__ __forceinline__ void xcd_barrier(const XcdBarrier& b) {
;     ...
;     if (threadIdx.x == 0) {
;         unsigned* bar = b.bar;
;         __builtin_amdgcn_s_waitcnt(0);
;         unsigned nloc = b.st[0], nx = b.st[1];
;         if (nloc == 0u) { xcd_barrier_complete(bar, b.x, nloc, nx); b.st[0] = nloc; b.st[1] = nx; }
;         const unsigned old = xb_add(&bar[XB_XSUB(b.x)], 1u);
;         const unsigned gen = old / nloc;
;         if (old + 1u == (gen + 1u) * nloc) {
;             __builtin_amdgcn_fence(__ATOMIC_RELEASE, "agent");
;             asm volatile("s_waitcnt vmcnt(0)" ::: "memory");
;             const unsigned og = xb_add(&bar[XB_TOP], 1u);
;             const unsigned tg = og / nx;
;             if (og + 1u == (tg + 1u) * nx) xb_add(&bar[XB_TOPGEN], 1u);
;             else XB_SPIN(xb_ld(&bar[XB_TOPGEN]) == tg, bar);
.Leinv_skip_3:
	s_mov_b64 s[0:1], exec
	v_readlane_b32 s2, v255, 2
	v_readlane_b32 s3, v255, 3
	s_and_b64 s[2:3], s[0:1], s[2:3]
	s_mov_b64 exec, s[2:3]
	s_cbranch_execz .LBB0_608
	v_mov_b32_e32 v0, 0x20000
	ds_read_b64 v[4:5], v0
	v_readlane_b32 s2, v255, 1
	s_lshl_b32 s2, s2, 8
	s_add_u32 s4, s96, s2
	s_addc_u32 s5, s97, 0
	v_mov_b32_e32 v3, 0x1000
	v_mov_b32_e32 v1, 1
	global_atomic_add v3, v3, v1, s[4:5] offset:1024 sc0
	v_mov_b32_e32 v2, 0x583000
	s_waitcnt lgkmcnt(0)
	v_mul_u32_u24_e32 v4, 4, v4
	v_mul_u32_u24_e32 v5, 4, v5
	s_nop 0
	v_readfirstlane_b32 s8, v5
	s_waitcnt vmcnt(0)
	v_readfirstlane_b32 s2, v3
	s_add_u32 s2, s2, 1
	v_cmp_ne_u32_e32 vcc, s2, v4
	s_cbranch_vccnz .Lgb_poll_3
	buffer_wbl2 sc1
	v_mov_b32_e32 v3, 1
	s_waitcnt vmcnt(0)
	global_atomic_add v2, v3, s[72:73] offset:1024

; __device__ __forceinline__ unsigned xb_ld(unsigned* p)              { return __hip_atomic_load(p, __ATOMIC_RELAXED, __HIP_MEMORY_SCOPE_AGENT); }
; __device__ __forceinline__ unsigned xb_add(unsigned* p, unsigned v) { return __hip_atomic_fetch_add(p, v, __ATOMIC_RELAXED, __HIP_MEMORY_SCOPE_AGENT); }
; #define XB_SPIN(cond, bar) do { unsigned _sp = 0; while (cond) { __builtin_amdgcn_s_sleep(1); \
;     if ((++_sp & 255u) == 0u) { if (xb_ld(&(bar)[XB_TMO])) break; if (_sp > XB_SPIN_CAP) { atomicAdd(&(bar)[XB_TMO], 1u); break; } } } } while (0)
; __device__ __forceinline__ void xcd_barrier(const XcdBarrier& b) {
;     ...
;     if (threadIdx.x == 0) {
;         unsigned* bar = b.bar;
;         __builtin_amdgcn_s_waitcnt(0);
;         unsigned nloc = b.st[0], nx = b.st[1];
;         if (nloc == 0u) { xcd_barrier_complete(bar, b.x, nloc, nx); b.st[0] = nloc; b.st[1] = nx; }
;         const unsigned old = xb_add(&bar[XB_XSUB(b.x)], 1u);
;         const unsigned gen = old / nloc;
;         if (old + 1u == (gen + 1u) * nloc) {
;             __builtin_amdgcn_fence(__ATOMIC_RELEASE, "agent");
;             asm volatile("s_waitcnt vmcnt(0)" ::: "memory");
;             const unsigned og = xb_add(&bar[XB_TOP], 1u);
;             const unsigned tg = og / nx;
;             if (og + 1u == (tg + 1u) * nx) xb_add(&bar[XB_TOPGEN], 1u);
;             else XB_SPIN(xb_ld(&bar[XB_TOPGEN]) == tg, bar);
.Leinv_skip_4:
	s_mov_b64 s[0:1], exec
	v_readlane_b32 s2, v255, 2
	v_readlane_b32 s3, v255, 3
	s_and_b64 s[2:3], s[0:1], s[2:3]
	s_mov_b64 exec, s[2:3]
	s_cbranch_execz .LBB0_1029
	v_mov_b32_e32 v0, 0x20000
	ds_read_b64 v[4:5], v0
	v_readlane_b32 s2, v255, 1
	s_lshl_b32 s2, s2, 8
	s_add_u32 s4, s96, s2
	s_addc_u32 s5, s97, 0
	v_mov_b32_e32 v3, 0x1000
	v_mov_b32_e32 v1, 1
	global_atomic_add v3, v3, v1, s[4:5] offset:1024 sc0
	v_mov_b32_e32 v2, 0x583000
	s_waitcnt lgkmcnt(0)
	v_mul_u32_u24_e32 v4, 5, v4
	v_mul_u32_u24_e32 v5, 5, v5
	s_nop 0
	v_readfirstlane_b32 s8, v5
	s_waitcnt vmcnt(0)
	v_readfirstlane_b32 s2, v3
	s_add_u32 s2, s2, 1
	v_cmp_ne_u32_e32 vcc, s2, v4
	s_cbranch_vccnz .Lgb_poll_4
	buffer_wbl2 sc1
	v_mov_b32_e32 v3, 1
	s_waitcnt vmcnt(0)
	global_atomic_add v2, v3, s[72:73] offset:1024

; __device__ __forceinline__ unsigned xb_ld(unsigned* p)              { return __hip_atomic_load(p, __ATOMIC_RELAXED, __HIP_MEMORY_SCOPE_AGENT); }
; __device__ __forceinline__ unsigned xb_add(unsigned* p, unsigned v) { return __hip_atomic_fetch_add(p, v, __ATOMIC_RELAXED, __HIP_MEMORY_SCOPE_AGENT); }
; #define XB_SPIN(cond, bar) do { unsigned _sp = 0; while (cond) { __builtin_amdgcn_s_sleep(1); \
;     if ((++_sp & 255u) == 0u) { if (xb_ld(&(bar)[XB_TMO])) break; if (_sp > XB_SPIN_CAP) { atomicAdd(&(bar)[XB_TMO], 1u); break; } } } } while (0)
; __device__ __forceinline__ void xcd_barrier(const XcdBarrier& b) {
;     ...
;     if (threadIdx.x == 0) {
;         unsigned* bar = b.bar;
;         __builtin_amdgcn_s_waitcnt(0);
;         unsigned nloc = b.st[0], nx = b.st[1];
;         if (nloc == 0u) { xcd_barrier_complete(bar, b.x, nloc, nx); b.st[0] = nloc; b.st[1] = nx; }
;         const unsigned old = xb_add(&bar[XB_XSUB(b.x)], 1u);
;         const unsigned gen = old / nloc;
;         if (old + 1u == (gen + 1u) * nloc) {
;             __builtin_amdgcn_fence(__ATOMIC_RELEASE, "agent");
;             asm volatile("s_waitcnt vmcnt(0)" ::: "memory");
;             const unsigned og = xb_add(&bar[XB_TOP], 1u);
;             const unsigned tg = og / nx;
;             if (og + 1u == (tg + 1u) * nx) xb_add(&bar[XB_TOPGEN], 1u);
;             else XB_SPIN(xb_ld(&bar[XB_TOPGEN]) == tg, bar);
.Leinv_skip_5:
	s_mov_b64 s[4:5], exec
	v_readlane_b32 s2, v255, 2
	v_readlane_b32 s3, v255, 3
	s_and_b64 s[2:3], s[4:5], s[2:3]
	s_mov_b64 exec, s[2:3]
	s_cbranch_execz .LBB0_1114
	v_mov_b32_e32 v0, 0x20000
	ds_read_b64 v[4:5], v0
	v_readlane_b32 s2, v255, 1
	s_lshl_b32 s2, s2, 8
	s_add_u32 s6, s96, s2
	s_addc_u32 s7, s97, 0
	v_mov_b32_e32 v3, 0x1000
	v_mov_b32_e32 v1, 1
	global_atomic_add v3, v3, v1, s[6:7] offset:1024 sc0
	v_mov_b32_e32 v2, 0x583000
	s_waitcnt lgkmcnt(0)
	v_mul_u32_u24_e32 v4, 6, v4
	v_mul_u32_u24_e32 v5, 6, v5
	s_nop 0
	v_readfirstlane_b32 s8, v5
	s_waitcnt vmcnt(0)
	v_readfirstlane_b32 s2, v3
	s_add_u32 s2, s2, 1
	v_cmp_ne_u32_e32 vcc, s2, v4
	s_cbranch_vccnz .Lgb_poll_5
	buffer_wbl2 sc1
	v_mov_b32_e32 v3, 1
	s_waitcnt vmcnt(0)
	global_atomic_add v2, v3, s[72:73] offset:1024

; __device__ __forceinline__ unsigned xb_ld(unsigned* p)              { return __hip_atomic_load(p, __ATOMIC_RELAXED, __HIP_MEMORY_SCOPE_AGENT); }
; __device__ __forceinline__ unsigned xb_add(unsigned* p, unsigned v) { return __hip_atomic_fetch_add(p, v, __ATOMIC_RELAXED, __HIP_MEMORY_SCOPE_AGENT); }
; #define XB_SPIN(cond, bar) do { unsigned _sp = 0; while (cond) { __builtin_amdgcn_s_sleep(1); \
;     if ((++_sp & 255u) == 0u) { if (xb_ld(&(bar)[XB_TMO])) break; if (_sp > XB_SPIN_CAP) { atomicAdd(&(bar)[XB_TMO], 1u); break; } } } } while (0)
; __device__ __forceinline__ void xcd_barrier(const XcdBarrier& b) {
;     ...
;     if (threadIdx.x == 0) {
;         unsigned* bar = b.bar;
;         __builtin_amdgcn_s_waitcnt(0);
;         unsigned nloc = b.st[0], nx = b.st[1];
;         if (nloc == 0u) { xcd_barrier_complete(bar, b.x, nloc, nx); b.st[0] = nloc; b.st[1] = nx; }
;         const unsigned old = xb_add(&bar[XB_XSUB(b.x)], 1u);
;         const unsigned gen = old / nloc;
;         if (old + 1u == (gen + 1u) * nloc) {
;             __builtin_amdgcn_fence(__ATOMIC_RELEASE, "agent");
;             asm volatile("s_waitcnt vmcnt(0)" ::: "memory");
;             const unsigned og = xb_add(&bar[XB_TOP], 1u);
;             const unsigned tg = og / nx;
;             if (og + 1u == (tg + 1u) * nx) xb_add(&bar[XB_TOPGEN], 1u);
;             else XB_SPIN(xb_ld(&bar[XB_TOPGEN]) == tg, bar);
.Leinv_skip_6:
	s_mov_b64 s[0:1], exec
	v_readlane_b32 s2, v255, 2
	v_readlane_b32 s3, v255, 3
	s_and_b64 s[2:3], s[0:1], s[2:3]
	s_mov_b64 exec, s[2:3]
	s_cbranch_execz .LBB0_1211
	v_mov_b32_e32 v0, 0x20000
	ds_read_b64 v[4:5], v0
	v_readlane_b32 s2, v255, 1
	s_lshl_b32 s2, s2, 8
	s_add_u32 s4, s96, s2
	s_addc_u32 s5, s97, 0
	v_mov_b32_e32 v3, 0x1000
	v_mov_b32_e32 v1, 1
	global_atomic_add v3, v3, v1, s[4:5] offset:1024 sc0
	v_mov_b32_e32 v2, 0x583000
	s_waitcnt lgkmcnt(0)
	v_mul_u32_u24_e32 v4, 7, v4
	v_mul_u32_u24_e32 v5, 7, v5
	s_nop 0
	v_readfirstlane_b32 s8, v5
	s_waitcnt vmcnt(0)
	v_readfirstlane_b32 s2, v3
	s_add_u32 s2, s2, 1
	v_cmp_ne_u32_e32 vcc, s2, v4
	s_cbranch_vccnz .Lgb_poll_6
	buffer_wbl2 sc1
	v_mov_b32_e32 v3, 1
	s_waitcnt vmcnt(0)
	global_atomic_add v2, v3, s[72:73] offset:1024

; __device__ __forceinline__ unsigned xb_ld(unsigned* p)              { return __hip_atomic_load(p, __ATOMIC_RELAXED, __HIP_MEMORY_SCOPE_AGENT); }
; __device__ __forceinline__ unsigned xb_add(unsigned* p, unsigned v) { return __hip_atomic_fetch_add(p, v, __ATOMIC_RELAXED, __HIP_MEMORY_SCOPE_AGENT); }
; #define XB_SPIN(cond, bar) do { unsigned _sp = 0; while (cond) { __builtin_amdgcn_s_sleep(1); \
;     if ((++_sp & 255u) == 0u) { if (xb_ld(&(bar)[XB_TMO])) break; if (_sp > XB_SPIN_CAP) { atomicAdd(&(bar)[XB_TMO], 1u); break; } } } } while (0)
; __device__ __forceinline__ void xcd_barrier(const XcdBarrier& b) {
;     ...
;     if (threadIdx.x == 0) {
;         unsigned* bar = b.bar;
;         __builtin_amdgcn_s_waitcnt(0);
;         unsigned nloc = b.st[0], nx = b.st[1];
;         if (nloc == 0u) { xcd_barrier_complete(bar, b.x, nloc, nx); b.st[0] = nloc; b.st[1] = nx; }
;         const unsigned old = xb_add(&bar[XB_XSUB(b.x)], 1u);
;         const unsigned gen = old / nloc;
;         if (old + 1u == (gen + 1u) * nloc) {
;             __builtin_amdgcn_fence(__ATOMIC_RELEASE, "agent");
;             asm volatile("s_waitcnt vmcnt(0)" ::: "memory");
;             const unsigned og = xb_add(&bar[XB_TOP], 1u);
;             const unsigned tg = og / nx;
;             if (og + 1u == (tg + 1u) * nx) xb_add(&bar[XB_TOPGEN], 1u);
;             else XB_SPIN(xb_ld(&bar[XB_TOPGEN]) == tg, bar);
.Leinv_skip_7:
	s_mov_b64 s[0:1], exec
	v_readlane_b32 s2, v255, 2
	v_readlane_b32 s3, v255, 3
	v_readlane_b32 s48, v255, 5
	s_and_b64 s[2:3], s[0:1], s[2:3]
	v_readlane_b32 s49, v255, 6
	s_mov_b64 exec, s[2:3]
	s_cbranch_execz .LBB0_1305
	v_mov_b32_e32 v0, 0x20000
	ds_read_b64 v[4:5], v0
	v_readlane_b32 s2, v255, 1
	s_lshl_b32 s2, s2, 8
	s_add_u32 s4, s96, s2
	s_addc_u32 s5, s97, 0
	v_mov_b32_e32 v3, 0x1000
	v_mov_b32_e32 v1, 1
	global_atomic_add v3, v3, v1, s[4:5] offset:1024 sc0
	v_mov_b32_e32 v2, 0x583000
	s_waitcnt lgkmcnt(0)
	v_mul_u32_u24_e32 v4, 8, v4
	v_mul_u32_u24_e32 v5, 8, v5
	s_nop 0
	v_readfirstlane_b32 s8, v5
	s_waitcnt vmcnt(0)
	v_readfirstlane_b32 s2, v3
	s_add_u32 s2, s2, 1
	v_cmp_ne_u32_e32 vcc, s2, v4
	s_cbranch_vccnz .Lgb_poll_7
	buffer_wbl2 sc1
	v_mov_b32_e32 v3, 1
	s_waitcnt vmcnt(0)
	global_atomic_add v2, v3, s[72:73] offset:1024

; __device__ __forceinline__ unsigned xb_ld(unsigned* p)              { return __hip_atomic_load(p, __ATOMIC_RELAXED, __HIP_MEMORY_SCOPE_AGENT); }
; __device__ __forceinline__ unsigned xb_add(unsigned* p, unsigned v) { return __hip_atomic_fetch_add(p, v, __ATOMIC_RELAXED, __HIP_MEMORY_SCOPE_AGENT); }
; #define XB_SPIN(cond, bar) do { unsigned _sp = 0; while (cond) { __builtin_amdgcn_s_sleep(1); \
;     if ((++_sp & 255u) == 0u) { if (xb_ld(&(bar)[XB_TMO])) break; if (_sp > XB_SPIN_CAP) { atomicAdd(&(bar)[XB_TMO], 1u); break; } } } } while (0)
; __device__ __forceinline__ void xcd_barrier(const XcdBarrier& b) {
;     ...
;     if (threadIdx.x == 0) {
;         unsigned* bar = b.bar;
;         __builtin_amdgcn_s_waitcnt(0);
;         unsigned nloc = b.st[0], nx = b.st[1];
;         if (nloc == 0u) { xcd_barrier_complete(bar, b.x, nloc, nx); b.st[0] = nloc; b.st[1] = nx; }
;         const unsigned old = xb_add(&bar[XB_XSUB(b.x)], 1u);
;         const unsigned gen = old / nloc;
;         if (old + 1u == (gen + 1u) * nloc) {
;             __builtin_amdgcn_fence(__ATOMIC_RELEASE, "agent");
;             asm volatile("s_waitcnt vmcnt(0)" ::: "memory");
;             const unsigned og = xb_add(&bar[XB_TOP], 1u);
;             const unsigned tg = og / nx;
;             if (og + 1u == (tg + 1u) * nx) xb_add(&bar[XB_TOPGEN], 1u);
;             else XB_SPIN(xb_ld(&bar[XB_TOPGEN]) == tg, bar);
.Leinv_skip_8:
	s_mov_b64 s[0:1], exec
	v_readlane_b32 s2, v255, 2
	v_readlane_b32 s3, v255, 3
	s_and_b64 s[2:3], s[0:1], s[2:3]
	s_mov_b64 exec, s[2:3]
	s_cbranch_execz .LBB0_1419
	v_mov_b32_e32 v0, 0x20000
	ds_read_b64 v[4:5], v0
	v_readlane_b32 s2, v255, 1
	s_lshl_b32 s2, s2, 8
	s_add_u32 s4, s96, s2
	s_addc_u32 s5, s97, 0
	v_mov_b32_e32 v3, 0x1000
	v_mov_b32_e32 v1, 1
	global_atomic_add v3, v3, v1, s[4:5] offset:1024 sc0
	v_mov_b32_e32 v2, 0x583000
	s_waitcnt lgkmcnt(0)
	v_mul_u32_u24_e32 v4, 9, v4
	v_mul_u32_u24_e32 v5, 9, v5
	s_nop 0
	v_readfirstlane_b32 s8, v5
	s_waitcnt vmcnt(0)
	v_readfirstlane_b32 s2, v3
	s_add_u32 s2, s2, 1
	v_cmp_ne_u32_e32 vcc, s2, v4
	s_cbranch_vccnz .Lgb_poll_8
	buffer_wbl2 sc1
	v_mov_b32_e32 v3, 1
	s_waitcnt vmcnt(0)
	global_atomic_add v2, v3, s[72:73] offset:1024
